# P2 queue: same prompt/sample attention interleave as baseline but the 130 short conv tiles moved to the END of the queue (tail fillers) instead of first
# speedup vs baseline: 1.0295x; 1.0295x over previous
.LBB0_448:
	s_or_b64 exec, exec, s[2:3]
	s_waitcnt lgkmcnt(0)
	s_barrier
	ds_read_b32 v3, v1
	s_mov_b64 s[2:3], -1
	s_waitcnt lgkmcnt(0)
	s_barrier
	v_readfirstlane_b32 s4, v3
	s_cmpk_gt_i32 s4, 0x381
	s_cbranch_scc1 .LBB0_439
	s_mov_b64 s[0:1], -1
	s_cmpk_lt_u32 s4, 0x300
	s_cbranch_scc1 .Lord_att
	s_sub_u32 s4, s4, 0x300
	s_branch .LBB0_519
.Lord_att:
	s_cmpk_lt_u32 s4, 192
	s_cbranch_scc0 .Lord_mid
	s_and_b32 s1, s4, 1
	s_lshr_b32 s0, s4, 1
	s_cmp_eq_u32 s1, 0
	s_cselect_b32 s2, -1, s0
	s_cselect_b32 s5, s0, -1
	s_branch .Lord_go
.Lord_mid:
	s_cmpk_lt_u32 s4, 624
	s_cbranch_scc0 .Lord_light
	s_sub_u32 s0, s4, 192
	s_mul_i32 s1, s0, 0xaaab
	s_lshr_b32 s1, s1, 17
	s_mul_i32 s2, s1, 3
	s_sub_u32 s0, s0, s2
	s_cmp_eq_u32 s0, 2
	s_cbranch_scc1 .Lord_mid_pa
	s_lshl_b32 s1, s1, 1
	s_add_u32 s2, s1, s0
	s_addk_i32 s2, 96
	s_mov_b32 s5, -1
	s_branch .Lord_go
.Lord_mid_pa:
	s_add_u32 s5, s1, 96
	s_mov_b32 s2, -1
	s_branch .Lord_go
.Lord_light:
	s_sub_u32 s5, s4, 384
	s_mov_b32 s2, -1
